# v040 plus third gMLP round moved to workgroups 192-255 (disjoint from the context-attention workgroups)
# speedup vs baseline: 1.0008x; 1.0008x over previous
.LBB0_274:
	s_bfe_u32 s0, s8, 0x30002
	s_lshl_b32 s1, s0, 14
	s_add_i32 s42, s6, s1
	s_and_b32 s1, s7, 0xffffff80
	v_or_b32_e32 v50, s1, v192
	s_lshl_b32 s0, s0, 7
	s_lshl_b32 s1, s8, 5
	v_lshl_add_u64 v[48:49], s[42:43], 1, v[44:45]
	s_add_i32 s42, s5, s0
	s_lshl_b32 s0, s8, 2
	s_and_b32 s9, s1, 0x3e0
	s_and_b32 s0, s0, 0xffffff80
	v_or_b32_e32 v22, s9, v193
	v_or_b32_e32 v2, s0, v67
	v_or_b32_e32 v194, s5, v22
	v_readlane_b32 s52, v252, 12
	v_ashrrev_i32_e32 v3, 31, v2
	v_lshlrev_b64 v[4:5], 2, v[194:195]
	v_readlane_b32 s53, v252, 13
	v_readlane_b32 s54, v252, 14
	v_readlane_b32 s55, v252, 15
	s_ashr_i32 s1, s0, 31
	v_lshl_add_u64 v[2:3], v[2:3], 3, s[2:3]
	v_lshl_add_u64 v[62:63], s[52:53], 0, v[4:5]
	v_lshl_add_u64 v[64:65], s[54:55], 0, v[4:5]
	v_mul_u32_u24_e32 v4, 0x4800, v22
	global_load_dwordx4 v[76:79], v[2:3], off
	global_load_dwordx4 v[80:83], v[2:3], off offset:16
	global_load_dwordx4 v[84:87], v[2:3], off offset:32
	global_load_dwordx4 v[88:91], v[2:3], off offset:48
	global_load_dwordx4 v[92:95], v[2:3], off offset:256
	global_load_dwordx4 v[96:99], v[2:3], off offset:272
	global_load_dwordx4 v[100:103], v[2:3], off offset:288
	global_load_dwordx4 v[104:107], v[2:3], off offset:304
	global_load_dwordx4 v[108:111], v[2:3], off offset:512
	global_load_dwordx4 v[112:115], v[2:3], off offset:528
	global_load_dwordx4 v[116:119], v[2:3], off offset:544
	global_load_dwordx4 v[120:123], v[2:3], off offset:560
	global_load_dwordx4 v[124:127], v[2:3], off offset:768
	global_load_dwordx4 v[128:131], v[2:3], off offset:784
	global_load_dwordx4 v[132:135], v[2:3], off offset:800
	global_load_dwordx4 v[136:139], v[2:3], off offset:816
	v_lshl_add_u64 v[2:3], s[0:1], 1, v[42:43]
	v_lshlrev_b32_e32 v194, 1, v4
	v_lshl_add_u64 v[60:61], v[2:3], 0, v[194:195]
	s_mov_b32 s1, 0x24000
	s_mov_b64 s[10:11], 0x24000
	v_lshl_add_u64 v[54:55], v[60:61], 0, s[10:11]
	v_lshl_add_u64 v[52:53], s[42:43], 2, v[46:47]
	global_load_dwordx4 v[140:143], v[60:61], off
	global_load_dwordx4 v[144:147], v[60:61], off offset:64
	global_load_dwordx4 v[148:151], v[60:61], off offset:128
	global_load_dwordx4 v[152:155], v[60:61], off offset:192
	global_load_dwordx4 v[156:159], v[54:55], off
	global_load_dwordx4 v[160:163], v[54:55], off offset:64
	global_load_dwordx4 v[164:167], v[54:55], off offset:128
	global_load_dwordx4 v[168:171], v[54:55], off offset:192
	global_load_dword v172, v[62:63], off
	global_load_dword v173, v[64:65], off
	global_load_dword v174, v[62:63], off offset:16
	global_load_dword v175, v[64:65], off offset:16
	v_readlane_b32 s56, v252, 16
	v_readlane_b32 s57, v252, 17
	v_readlane_b32 s58, v252, 18
	v_readlane_b32 s59, v252, 19
	v_readlane_b32 s60, v252, 20
	v_readlane_b32 s61, v252, 21
	v_readlane_b32 s62, v252, 22
	v_readlane_b32 s63, v252, 23
	v_readlane_b32 s64, v252, 24
	v_readlane_b32 s65, v252, 25
	v_readlane_b32 s66, v252, 26
	v_readlane_b32 s67, v252, 27
	v_readlane_b32 s0, v251, 35
	v_readlane_b32 s1, v251, 36
	s_waitcnt vmcnt(0)
	v_lshlrev_b32_e32 v34, 16, v140
	v_and_b32_e32 v35, 0xffff0000, v140
	v_sub_f32_e32 v34, v34, v76
	v_sub_f32_e32 v35, v35, v78
	v_mul_f32_e32 v34, v77, v34
	v_mul_f32_e32 v35, v79, v35
	v_fma_f32 v34, v172, v34, v173
	v_fma_f32 v35, v172, v35, v173
	v_cvt_pk_bf16_f32 v2, v34, v35
	v_lshlrev_b32_e32 v34, 16, v141
	v_and_b32_e32 v35, 0xffff0000, v141
	v_sub_f32_e32 v34, v34, v80
	v_sub_f32_e32 v35, v35, v82
	v_mul_f32_e32 v34, v81, v34
	v_mul_f32_e32 v35, v83, v35
	v_fma_f32 v34, v172, v34, v173
	v_fma_f32 v35, v172, v35, v173
	v_cvt_pk_bf16_f32 v3, v34, v35
	v_lshlrev_b32_e32 v34, 16, v142
	v_and_b32_e32 v35, 0xffff0000, v142
	v_sub_f32_e32 v34, v34, v84
	v_sub_f32_e32 v35, v35, v86
	v_mul_f32_e32 v34, v85, v34
	v_mul_f32_e32 v35, v87, v35
	v_fma_f32 v34, v172, v34, v173
	v_fma_f32 v35, v172, v35, v173
	v_cvt_pk_bf16_f32 v4, v34, v35
	v_lshlrev_b32_e32 v34, 16, v143
	v_and_b32_e32 v35, 0xffff0000, v143
	v_sub_f32_e32 v34, v34, v88
	v_sub_f32_e32 v35, v35, v90
	v_mul_f32_e32 v34, v89, v34
	v_mul_f32_e32 v35, v91, v35
	v_fma_f32 v34, v172, v34, v173
	v_fma_f32 v35, v172, v35, v173
	v_cvt_pk_bf16_f32 v5, v34, v35
	v_lshlrev_b32_e32 v34, 16, v156
	v_and_b32_e32 v35, 0xffff0000, v156
	v_sub_f32_e32 v34, v34, v76
	v_sub_f32_e32 v35, v35, v78
	v_mul_f32_e32 v34, v77, v34
	v_mul_f32_e32 v35, v79, v35
	v_fma_f32 v34, v174, v34, v175
	v_fma_f32 v35, v174, v35, v175
	v_cvt_pk_bf16_f32 v6, v34, v35
	v_lshlrev_b32_e32 v34, 16, v157
	v_and_b32_e32 v35, 0xffff0000, v157
	v_sub_f32_e32 v34, v34, v80
	v_sub_f32_e32 v35, v35, v82
	v_mul_f32_e32 v34, v81, v34
	v_mul_f32_e32 v35, v83, v35
	v_fma_f32 v34, v174, v34, v175
	v_fma_f32 v35, v174, v35, v175
	v_cvt_pk_bf16_f32 v7, v34, v35
	v_lshlrev_b32_e32 v34, 16, v158
	v_and_b32_e32 v35, 0xffff0000, v158
	v_sub_f32_e32 v34, v34, v84
	v_sub_f32_e32 v35, v35, v86
	v_mul_f32_e32 v34, v85, v34
	v_mul_f32_e32 v35, v87, v35
	v_fma_f32 v34, v174, v34, v175
	v_fma_f32 v35, v174, v35, v175
	v_cvt_pk_bf16_f32 v8, v34, v35
	v_lshlrev_b32_e32 v34, 16, v159
	v_and_b32_e32 v35, 0xffff0000, v159
	v_sub_f32_e32 v34, v34, v88
	v_sub_f32_e32 v35, v35, v90
	v_mul_f32_e32 v34, v89, v34
	v_mul_f32_e32 v35, v91, v35
	v_fma_f32 v34, v174, v34, v175
	v_fma_f32 v35, v174, v35, v175
	v_cvt_pk_bf16_f32 v9, v34, v35
	v_lshlrev_b32_e32 v34, 16, v144
	v_and_b32_e32 v35, 0xffff0000, v144
	v_sub_f32_e32 v34, v34, v92
	v_sub_f32_e32 v35, v35, v94
	v_mul_f32_e32 v34, v93, v34
	v_mul_f32_e32 v35, v95, v35
	v_fma_f32 v34, v172, v34, v173
	v_fma_f32 v35, v172, v35, v173
	v_cvt_pk_bf16_f32 v10, v34, v35
	v_lshlrev_b32_e32 v34, 16, v145
	v_and_b32_e32 v35, 0xffff0000, v145
	v_sub_f32_e32 v34, v34, v96
	v_sub_f32_e32 v35, v35, v98
	v_mul_f32_e32 v34, v97, v34
	v_mul_f32_e32 v35, v99, v35
	v_fma_f32 v34, v172, v34, v173
	v_fma_f32 v35, v172, v35, v173
	v_cvt_pk_bf16_f32 v11, v34, v35
	v_lshlrev_b32_e32 v34, 16, v146
	v_and_b32_e32 v35, 0xffff0000, v146
	v_sub_f32_e32 v34, v34, v100
	v_sub_f32_e32 v35, v35, v102
	v_mul_f32_e32 v34, v101, v34
	v_mul_f32_e32 v35, v103, v35
	v_fma_f32 v34, v172, v34, v173
	v_fma_f32 v35, v172, v35, v173
	v_cvt_pk_bf16_f32 v12, v34, v35
	v_lshlrev_b32_e32 v34, 16, v147
	v_and_b32_e32 v35, 0xffff0000, v147
	v_sub_f32_e32 v34, v34, v104
	v_sub_f32_e32 v35, v35, v106
	v_mul_f32_e32 v34, v105, v34
	v_mul_f32_e32 v35, v107, v35
	v_fma_f32 v34, v172, v34, v173
	v_fma_f32 v35, v172, v35, v173
	v_cvt_pk_bf16_f32 v13, v34, v35
	v_lshlrev_b32_e32 v34, 16, v160
	v_and_b32_e32 v35, 0xffff0000, v160
	v_sub_f32_e32 v34, v34, v92
	v_sub_f32_e32 v35, v35, v94
	v_mul_f32_e32 v34, v93, v34
	v_mul_f32_e32 v35, v95, v35
	v_fma_f32 v34, v174, v34, v175
	v_fma_f32 v35, v174, v35, v175
	v_cvt_pk_bf16_f32 v14, v34, v35
	v_lshlrev_b32_e32 v34, 16, v161
	v_and_b32_e32 v35, 0xffff0000, v161
	v_sub_f32_e32 v34, v34, v96
	v_sub_f32_e32 v35, v35, v98
	v_mul_f32_e32 v34, v97, v34
	v_mul_f32_e32 v35, v99, v35
	v_fma_f32 v34, v174, v34, v175
	v_fma_f32 v35, v174, v35, v175
	v_cvt_pk_bf16_f32 v15, v34, v35
	v_lshlrev_b32_e32 v34, 16, v162
	v_and_b32_e32 v35, 0xffff0000, v162
	v_sub_f32_e32 v34, v34, v100
	v_sub_f32_e32 v35, v35, v102
	v_mul_f32_e32 v34, v101, v34
	v_mul_f32_e32 v35, v103, v35
	v_fma_f32 v34, v174, v34, v175
	v_fma_f32 v35, v174, v35, v175
	v_cvt_pk_bf16_f32 v16, v34, v35
	v_lshlrev_b32_e32 v34, 16, v163
	v_and_b32_e32 v35, 0xffff0000, v163
	v_sub_f32_e32 v34, v34, v104
	v_sub_f32_e32 v35, v35, v106
	v_mul_f32_e32 v34, v105, v34
	v_mul_f32_e32 v35, v107, v35
	v_fma_f32 v34, v174, v34, v175
	v_fma_f32 v35, v174, v35, v175
	v_cvt_pk_bf16_f32 v17, v34, v35
	v_lshlrev_b32_e32 v34, 16, v148
	v_and_b32_e32 v35, 0xffff0000, v148
	v_sub_f32_e32 v34, v34, v108
	v_sub_f32_e32 v35, v35, v110
	v_mul_f32_e32 v34, v109, v34
	v_mul_f32_e32 v35, v111, v35
	v_fma_f32 v34, v172, v34, v173
	v_fma_f32 v35, v172, v35, v173
	v_cvt_pk_bf16_f32 v18, v34, v35
	v_lshlrev_b32_e32 v34, 16, v149
	v_and_b32_e32 v35, 0xffff0000, v149
	v_sub_f32_e32 v34, v34, v112
	v_sub_f32_e32 v35, v35, v114
	v_mul_f32_e32 v34, v113, v34
	v_mul_f32_e32 v35, v115, v35
	v_fma_f32 v34, v172, v34, v173
	v_fma_f32 v35, v172, v35, v173
	v_cvt_pk_bf16_f32 v19, v34, v35
	v_lshlrev_b32_e32 v34, 16, v150
	v_and_b32_e32 v35, 0xffff0000, v150
	v_sub_f32_e32 v34, v34, v116
	v_sub_f32_e32 v35, v35, v118
	v_mul_f32_e32 v34, v117, v34
	v_mul_f32_e32 v35, v119, v35
	v_fma_f32 v34, v172, v34, v173
	v_fma_f32 v35, v172, v35, v173
	v_cvt_pk_bf16_f32 v20, v34, v35
	v_lshlrev_b32_e32 v34, 16, v151
	v_and_b32_e32 v35, 0xffff0000, v151
	v_sub_f32_e32 v34, v34, v120
	v_sub_f32_e32 v35, v35, v122
	v_mul_f32_e32 v34, v121, v34
	v_mul_f32_e32 v35, v123, v35
	v_fma_f32 v34, v172, v34, v173
	v_fma_f32 v35, v172, v35, v173
	v_cvt_pk_bf16_f32 v21, v34, v35
	v_lshlrev_b32_e32 v34, 16, v164
	v_and_b32_e32 v35, 0xffff0000, v164
	v_sub_f32_e32 v34, v34, v108
	v_sub_f32_e32 v35, v35, v110
	v_mul_f32_e32 v34, v109, v34
	v_mul_f32_e32 v35, v111, v35
	v_fma_f32 v34, v174, v34, v175
	v_fma_f32 v35, v174, v35, v175
	v_cvt_pk_bf16_f32 v22, v34, v35
	v_lshlrev_b32_e32 v34, 16, v165
	v_and_b32_e32 v35, 0xffff0000, v165
	v_sub_f32_e32 v34, v34, v112
	v_sub_f32_e32 v35, v35, v114
	v_mul_f32_e32 v34, v113, v34
	v_mul_f32_e32 v35, v115, v35
	v_fma_f32 v34, v174, v34, v175
	v_fma_f32 v35, v174, v35, v175
	v_cvt_pk_bf16_f32 v23, v34, v35
	v_lshlrev_b32_e32 v34, 16, v166
	v_and_b32_e32 v35, 0xffff0000, v166
	v_sub_f32_e32 v34, v34, v116
	v_sub_f32_e32 v35, v35, v118
	v_mul_f32_e32 v34, v117, v34
	v_mul_f32_e32 v35, v119, v35
	v_fma_f32 v34, v174, v34, v175
	v_fma_f32 v35, v174, v35, v175
	v_cvt_pk_bf16_f32 v24, v34, v35
	v_lshlrev_b32_e32 v34, 16, v167
	v_and_b32_e32 v35, 0xffff0000, v167
	v_sub_f32_e32 v34, v34, v120
	v_sub_f32_e32 v35, v35, v122
	v_mul_f32_e32 v34, v121, v34
	v_mul_f32_e32 v35, v123, v35
	v_fma_f32 v34, v174, v34, v175
	v_fma_f32 v35, v174, v35, v175
	v_cvt_pk_bf16_f32 v25, v34, v35
	v_lshlrev_b32_e32 v34, 16, v152
	v_and_b32_e32 v35, 0xffff0000, v152
	v_sub_f32_e32 v34, v34, v124
	v_sub_f32_e32 v35, v35, v126
	v_mul_f32_e32 v34, v125, v34
	v_mul_f32_e32 v35, v127, v35
	v_fma_f32 v34, v172, v34, v173
	v_fma_f32 v35, v172, v35, v173
	v_cvt_pk_bf16_f32 v26, v34, v35
	v_lshlrev_b32_e32 v34, 16, v153
	v_and_b32_e32 v35, 0xffff0000, v153
	v_sub_f32_e32 v34, v34, v128
	v_sub_f32_e32 v35, v35, v130
	v_mul_f32_e32 v34, v129, v34
	v_mul_f32_e32 v35, v131, v35
	v_fma_f32 v34, v172, v34, v173
	v_fma_f32 v35, v172, v35, v173
	v_cvt_pk_bf16_f32 v27, v34, v35
	v_lshlrev_b32_e32 v34, 16, v154
	v_and_b32_e32 v35, 0xffff0000, v154
	v_sub_f32_e32 v34, v34, v132
	v_sub_f32_e32 v35, v35, v134
	v_mul_f32_e32 v34, v133, v34
	v_mul_f32_e32 v35, v135, v35
	v_fma_f32 v34, v172, v34, v173
	v_fma_f32 v35, v172, v35, v173
	v_cvt_pk_bf16_f32 v28, v34, v35
	v_lshlrev_b32_e32 v34, 16, v155
	v_and_b32_e32 v35, 0xffff0000, v155
	v_sub_f32_e32 v34, v34, v136
	v_sub_f32_e32 v35, v35, v138
	v_mul_f32_e32 v34, v137, v34
	v_mul_f32_e32 v35, v139, v35
	v_fma_f32 v34, v172, v34, v173
	v_fma_f32 v35, v172, v35, v173
	v_cvt_pk_bf16_f32 v29, v34, v35
	v_lshlrev_b32_e32 v34, 16, v168
	v_and_b32_e32 v35, 0xffff0000, v168
	v_sub_f32_e32 v34, v34, v124
	v_sub_f32_e32 v35, v35, v126
	v_mul_f32_e32 v34, v125, v34
	v_mul_f32_e32 v35, v127, v35
	v_fma_f32 v34, v174, v34, v175
	v_fma_f32 v35, v174, v35, v175
	v_cvt_pk_bf16_f32 v30, v34, v35
	v_lshlrev_b32_e32 v34, 16, v169
	v_and_b32_e32 v35, 0xffff0000, v169
	v_sub_f32_e32 v34, v34, v128
	v_sub_f32_e32 v35, v35, v130
	v_mul_f32_e32 v34, v129, v34
	v_mul_f32_e32 v35, v131, v35
	v_fma_f32 v34, v174, v34, v175
	v_fma_f32 v35, v174, v35, v175
	v_cvt_pk_bf16_f32 v31, v34, v35
	v_lshlrev_b32_e32 v34, 16, v170
	v_and_b32_e32 v35, 0xffff0000, v170
	v_sub_f32_e32 v34, v34, v132
	v_sub_f32_e32 v35, v35, v134
	v_mul_f32_e32 v34, v133, v34
	v_mul_f32_e32 v35, v135, v35
	v_fma_f32 v34, v174, v34, v175
	v_fma_f32 v35, v174, v35, v175
	v_cvt_pk_bf16_f32 v32, v34, v35
	v_lshlrev_b32_e32 v34, 16, v171
	v_and_b32_e32 v35, 0xffff0000, v171
	v_sub_f32_e32 v34, v34, v136
	v_sub_f32_e32 v35, v35, v138
	v_mul_f32_e32 v34, v137, v34
	v_mul_f32_e32 v35, v139, v35
	v_fma_f32 v34, v174, v34, v175
	v_fma_f32 v35, v174, v35, v175
	v_cvt_pk_bf16_f32 v33, v34, v35
	v_or_b32_e32 v34, s9, v67
	v_lshlrev_b32_e32 v194, 1, v34
	v_lshl_add_u64 v[54:55], s[0:1], 0, v[194:195]
	v_lshl_add_u64 v[56:57], s[50:51], 0, v[194:195]
	global_load_dword v172, v[52:53], off offset:-64
	v_mov_b32_e32 v180, v50
	v_mad_i64_i32 v[176:177], s[10:11], v180, s37, v[56:57]
	global_load_dwordx4 v[140:143], v[176:177], off
	global_load_dwordx4 v[156:159], v[176:177], off offset:2048
	global_load_dword v173, v[52:53], off offset:0
	v_add_u32_e32 v180, 16, v50
	v_mad_i64_i32 v[176:177], s[10:11], v180, s37, v[56:57]
	global_load_dwordx4 v[144:147], v[176:177], off
	global_load_dwordx4 v[160:163], v[176:177], off offset:2048
	global_load_dword v174, v[52:53], off offset:64
	v_add_u32_e32 v180, 32, v50
	v_mad_i64_i32 v[176:177], s[10:11], v180, s37, v[56:57]
	global_load_dwordx4 v[148:151], v[176:177], off
	global_load_dwordx4 v[164:167], v[176:177], off offset:2048
	global_load_dword v175, v[52:53], off offset:128
	v_add_u32_e32 v180, 48, v50
	v_mad_i64_i32 v[176:177], s[10:11], v180, s37, v[56:57]
	global_load_dwordx4 v[152:155], v[176:177], off
	global_load_dwordx4 v[168:171], v[176:177], off offset:2048
	ds_read_b128 v[76:79], v182
	ds_read_b128 v[80:83], v183
	ds_read_b128 v[84:87], v184
	ds_read_b128 v[88:91], v185
	ds_read_b128 v[92:95], v182 offset:4096
	ds_read_b128 v[96:99], v183 offset:4096
	ds_read_b128 v[100:103], v184 offset:4096
	ds_read_b128 v[104:107], v185 offset:4096
	ds_read_b128 v[108:111], v182 offset:8192
	ds_read_b128 v[112:115], v183 offset:8192
	ds_read_b128 v[116:119], v184 offset:8192
	ds_read_b128 v[120:123], v185 offset:8192
	ds_read_b128 v[124:127], v182 offset:12288
	ds_read_b128 v[128:131], v183 offset:12288
	ds_read_b128 v[132:135], v184 offset:12288
	ds_read_b128 v[136:139], v185 offset:12288
	s_waitcnt vmcnt(9) lgkmcnt(12)
	v_mfma_f32_16x16x32_bf16 v[38:41], v[2:5], v[76:79], 0
	v_mfma_f32_16x16x32_bf16 v[34:37], v[6:9], v[76:79], 0
	v_mfma_f32_16x16x32_bf16 v[38:41], v[10:13], v[80:83], v[38:41]
	v_mfma_f32_16x16x32_bf16 v[34:37], v[14:17], v[80:83], v[34:37]
	v_mfma_f32_16x16x32_bf16 v[38:41], v[18:21], v[84:87], v[38:41]
	v_mfma_f32_16x16x32_bf16 v[34:37], v[22:25], v[84:87], v[34:37]
	v_mfma_f32_16x16x32_bf16 v[38:41], v[26:29], v[88:91], v[38:41]
	v_mfma_f32_16x16x32_bf16 v[34:37], v[30:33], v[88:91], v[34:37]
	v_mov_b32_e32 v180, v50
	v_ashrrev_i32_e32 v181, 31, v180
	v_lshlrev_b64 v[178:179], 11, v[180:181]
	v_lshl_add_u64 v[178:179], v[54:55], 0, v[178:179]
	s_nop 7
	v_add_f32_e32 v62, v38, v172
	v_add_f32_e32 v63, v39, v172
	v_lshlrev_b32_e32 v64, 16, v140
	v_and_b32_e32 v65, 0xffff0000, v140
	v_mul_f32_e32 v62, v62, v64
	v_mul_f32_e32 v63, v63, v65
	v_lshlrev_b32_e32 v64, 16, v156
	v_and_b32_e32 v65, 0xffff0000, v156
	v_mul_f32_e32 v62, v62, v64
	v_mul_f32_e32 v63, v63, v65
	v_cvt_pk_bf16_f32 v58, v62, v63
	v_add_f32_e32 v62, v40, v172
	v_add_f32_e32 v63, v41, v172
	v_lshlrev_b32_e32 v64, 16, v141
	v_and_b32_e32 v65, 0xffff0000, v141
	v_mul_f32_e32 v62, v62, v64
	v_mul_f32_e32 v63, v63, v65
	v_lshlrev_b32_e32 v64, 16, v157
	v_and_b32_e32 v65, 0xffff0000, v157
	v_mul_f32_e32 v62, v62, v64
	v_mul_f32_e32 v63, v63, v65
	v_cvt_pk_bf16_f32 v59, v62, v63
	v_add_f32_e32 v62, v34, v172
	v_add_f32_e32 v63, v35, v172
	v_lshlrev_b32_e32 v64, 16, v142
	v_and_b32_e32 v65, 0xffff0000, v142
	v_mul_f32_e32 v62, v62, v64
	v_mul_f32_e32 v63, v63, v65
	v_lshlrev_b32_e32 v64, 16, v158
	v_and_b32_e32 v65, 0xffff0000, v158
	v_mul_f32_e32 v62, v62, v64
	v_mul_f32_e32 v63, v63, v65
	v_cvt_pk_bf16_f32 v60, v62, v63
	v_add_f32_e32 v62, v36, v172
	v_add_f32_e32 v63, v37, v172
	v_lshlrev_b32_e32 v64, 16, v143
	v_and_b32_e32 v65, 0xffff0000, v143
	v_mul_f32_e32 v62, v62, v64
	v_mul_f32_e32 v63, v63, v65
	v_lshlrev_b32_e32 v64, 16, v159
	v_and_b32_e32 v65, 0xffff0000, v159
	v_mul_f32_e32 v62, v62, v64
	v_mul_f32_e32 v63, v63, v65
	v_cvt_pk_bf16_f32 v61, v62, v63
	global_store_dwordx4 v[178:179], v[58:61], off
	s_waitcnt vmcnt(7) lgkmcnt(8)
	v_mfma_f32_16x16x32_bf16 v[38:41], v[2:5], v[92:95], 0
	v_mfma_f32_16x16x32_bf16 v[34:37], v[6:9], v[92:95], 0
	v_mfma_f32_16x16x32_bf16 v[38:41], v[10:13], v[96:99], v[38:41]
	v_mfma_f32_16x16x32_bf16 v[34:37], v[14:17], v[96:99], v[34:37]
	v_mfma_f32_16x16x32_bf16 v[38:41], v[18:21], v[100:103], v[38:41]
	v_mfma_f32_16x16x32_bf16 v[34:37], v[22:25], v[100:103], v[34:37]
	v_mfma_f32_16x16x32_bf16 v[38:41], v[26:29], v[104:107], v[38:41]
	v_mfma_f32_16x16x32_bf16 v[34:37], v[30:33], v[104:107], v[34:37]
	v_add_u32_e32 v180, 16, v50
	v_ashrrev_i32_e32 v181, 31, v180
	v_lshlrev_b64 v[178:179], 11, v[180:181]
	v_lshl_add_u64 v[178:179], v[54:55], 0, v[178:179]
	s_nop 7
	v_add_f32_e32 v62, v38, v173
	v_add_f32_e32 v63, v39, v173
	v_lshlrev_b32_e32 v64, 16, v144
	v_and_b32_e32 v65, 0xffff0000, v144
	v_mul_f32_e32 v62, v62, v64
	v_mul_f32_e32 v63, v63, v65
	v_lshlrev_b32_e32 v64, 16, v160
	v_and_b32_e32 v65, 0xffff0000, v160
	v_mul_f32_e32 v62, v62, v64
	v_mul_f32_e32 v63, v63, v65
	v_cvt_pk_bf16_f32 v58, v62, v63
	v_add_f32_e32 v62, v40, v173
	v_add_f32_e32 v63, v41, v173
	v_lshlrev_b32_e32 v64, 16, v145
	v_and_b32_e32 v65, 0xffff0000, v145
	v_mul_f32_e32 v62, v62, v64
	v_mul_f32_e32 v63, v63, v65
	v_lshlrev_b32_e32 v64, 16, v161
	v_and_b32_e32 v65, 0xffff0000, v161
	v_mul_f32_e32 v62, v62, v64
	v_mul_f32_e32 v63, v63, v65
	v_cvt_pk_bf16_f32 v59, v62, v63
	v_add_f32_e32 v62, v34, v173
	v_add_f32_e32 v63, v35, v173
	v_lshlrev_b32_e32 v64, 16, v146
	v_and_b32_e32 v65, 0xffff0000, v146
	v_mul_f32_e32 v62, v62, v64
	v_mul_f32_e32 v63, v63, v65
	v_lshlrev_b32_e32 v64, 16, v162
	v_and_b32_e32 v65, 0xffff0000, v162
	v_mul_f32_e32 v62, v62, v64
	v_mul_f32_e32 v63, v63, v65
	v_cvt_pk_bf16_f32 v60, v62, v63
	v_add_f32_e32 v62, v36, v173
	v_add_f32_e32 v63, v37, v173
	v_lshlrev_b32_e32 v64, 16, v147
	v_and_b32_e32 v65, 0xffff0000, v147
	v_mul_f32_e32 v62, v62, v64
	v_mul_f32_e32 v63, v63, v65
	v_lshlrev_b32_e32 v64, 16, v163
	v_and_b32_e32 v65, 0xffff0000, v163
	v_mul_f32_e32 v62, v62, v64
	v_mul_f32_e32 v63, v63, v65
	v_cvt_pk_bf16_f32 v61, v62, v63
	global_store_dwordx4 v[178:179], v[58:61], off
	s_waitcnt vmcnt(5) lgkmcnt(4)
	v_mfma_f32_16x16x32_bf16 v[38:41], v[2:5], v[108:111], 0
	v_mfma_f32_16x16x32_bf16 v[34:37], v[6:9], v[108:111], 0
	v_mfma_f32_16x16x32_bf16 v[38:41], v[10:13], v[112:115], v[38:41]
	v_mfma_f32_16x16x32_bf16 v[34:37], v[14:17], v[112:115], v[34:37]
	v_mfma_f32_16x16x32_bf16 v[38:41], v[18:21], v[116:119], v[38:41]
	v_mfma_f32_16x16x32_bf16 v[34:37], v[22:25], v[116:119], v[34:37]
	v_mfma_f32_16x16x32_bf16 v[38:41], v[26:29], v[120:123], v[38:41]
	v_mfma_f32_16x16x32_bf16 v[34:37], v[30:33], v[120:123], v[34:37]
	v_add_u32_e32 v180, 32, v50
	v_ashrrev_i32_e32 v181, 31, v180
	v_lshlrev_b64 v[178:179], 11, v[180:181]
	v_lshl_add_u64 v[178:179], v[54:55], 0, v[178:179]
	s_nop 7
	v_add_f32_e32 v62, v38, v174
	v_add_f32_e32 v63, v39, v174
	v_lshlrev_b32_e32 v64, 16, v148
	v_and_b32_e32 v65, 0xffff0000, v148
	v_mul_f32_e32 v62, v62, v64
	v_mul_f32_e32 v63, v63, v65
	v_lshlrev_b32_e32 v64, 16, v164
	v_and_b32_e32 v65, 0xffff0000, v164
	v_mul_f32_e32 v62, v62, v64
	v_mul_f32_e32 v63, v63, v65
	v_cvt_pk_bf16_f32 v58, v62, v63
	v_add_f32_e32 v62, v40, v174
	v_add_f32_e32 v63, v41, v174
	v_lshlrev_b32_e32 v64, 16, v149
	v_and_b32_e32 v65, 0xffff0000, v149
	v_mul_f32_e32 v62, v62, v64
	v_mul_f32_e32 v63, v63, v65
	v_lshlrev_b32_e32 v64, 16, v165
	v_and_b32_e32 v65, 0xffff0000, v165
	v_mul_f32_e32 v62, v62, v64
	v_mul_f32_e32 v63, v63, v65
	v_cvt_pk_bf16_f32 v59, v62, v63
	v_add_f32_e32 v62, v34, v174
	v_add_f32_e32 v63, v35, v174
	v_lshlrev_b32_e32 v64, 16, v150
	v_and_b32_e32 v65, 0xffff0000, v150
	v_mul_f32_e32 v62, v62, v64
	v_mul_f32_e32 v63, v63, v65
	v_lshlrev_b32_e32 v64, 16, v166
	v_and_b32_e32 v65, 0xffff0000, v166
	v_mul_f32_e32 v62, v62, v64
	v_mul_f32_e32 v63, v63, v65
	v_cvt_pk_bf16_f32 v60, v62, v63
	v_add_f32_e32 v62, v36, v174
	v_add_f32_e32 v63, v37, v174
	v_lshlrev_b32_e32 v64, 16, v151
	v_and_b32_e32 v65, 0xffff0000, v151
	v_mul_f32_e32 v62, v62, v64
	v_mul_f32_e32 v63, v63, v65
	v_lshlrev_b32_e32 v64, 16, v167
	v_and_b32_e32 v65, 0xffff0000, v167
	v_mul_f32_e32 v62, v62, v64
	v_mul_f32_e32 v63, v63, v65
	v_cvt_pk_bf16_f32 v61, v62, v63
	global_store_dwordx4 v[178:179], v[58:61], off
	s_waitcnt vmcnt(3) lgkmcnt(0)
	v_mfma_f32_16x16x32_bf16 v[38:41], v[2:5], v[124:127], 0
	v_mfma_f32_16x16x32_bf16 v[34:37], v[6:9], v[124:127], 0
	v_mfma_f32_16x16x32_bf16 v[38:41], v[10:13], v[128:131], v[38:41]
	v_mfma_f32_16x16x32_bf16 v[34:37], v[14:17], v[128:131], v[34:37]
	v_mfma_f32_16x16x32_bf16 v[38:41], v[18:21], v[132:135], v[38:41]
	v_mfma_f32_16x16x32_bf16 v[34:37], v[22:25], v[132:135], v[34:37]
	v_mfma_f32_16x16x32_bf16 v[38:41], v[26:29], v[136:139], v[38:41]
	v_mfma_f32_16x16x32_bf16 v[34:37], v[30:33], v[136:139], v[34:37]
	v_add_u32_e32 v180, 48, v50
	v_ashrrev_i32_e32 v181, 31, v180
	v_lshlrev_b64 v[178:179], 11, v[180:181]
	v_lshl_add_u64 v[178:179], v[54:55], 0, v[178:179]
	s_nop 7
	v_add_f32_e32 v62, v38, v175
	v_add_f32_e32 v63, v39, v175
	v_lshlrev_b32_e32 v64, 16, v152
	v_and_b32_e32 v65, 0xffff0000, v152
	v_mul_f32_e32 v62, v62, v64
	v_mul_f32_e32 v63, v63, v65
	v_lshlrev_b32_e32 v64, 16, v168
	v_and_b32_e32 v65, 0xffff0000, v168
	v_mul_f32_e32 v62, v62, v64
	v_mul_f32_e32 v63, v63, v65
	v_cvt_pk_bf16_f32 v58, v62, v63
	v_add_f32_e32 v62, v40, v175
	v_add_f32_e32 v63, v41, v175
	v_lshlrev_b32_e32 v64, 16, v153
	v_and_b32_e32 v65, 0xffff0000, v153
	v_mul_f32_e32 v62, v62, v64
	v_mul_f32_e32 v63, v63, v65
	v_lshlrev_b32_e32 v64, 16, v169
	v_and_b32_e32 v65, 0xffff0000, v169
	v_mul_f32_e32 v62, v62, v64
	v_mul_f32_e32 v63, v63, v65
	v_cvt_pk_bf16_f32 v59, v62, v63
	v_add_f32_e32 v62, v34, v175
	v_add_f32_e32 v63, v35, v175
	v_lshlrev_b32_e32 v64, 16, v154
	v_and_b32_e32 v65, 0xffff0000, v154
	v_mul_f32_e32 v62, v62, v64
	v_mul_f32_e32 v63, v63, v65
	v_lshlrev_b32_e32 v64, 16, v170
	v_and_b32_e32 v65, 0xffff0000, v170
	v_mul_f32_e32 v62, v62, v64
	v_mul_f32_e32 v63, v63, v65
	v_cvt_pk_bf16_f32 v60, v62, v63
	v_add_f32_e32 v62, v36, v175
	v_add_f32_e32 v63, v37, v175
	v_lshlrev_b32_e32 v64, 16, v155
	v_and_b32_e32 v65, 0xffff0000, v155
	v_mul_f32_e32 v62, v62, v64
	v_mul_f32_e32 v63, v63, v65
	v_lshlrev_b32_e32 v64, 16, v171
	v_and_b32_e32 v65, 0xffff0000, v171
	v_mul_f32_e32 v62, v62, v64
	v_mul_f32_e32 v63, v63, v65
	v_cvt_pk_bf16_f32 v61, v62, v63
	global_store_dwordx4 v[178:179], v[58:61], off
	global_load_dword v172, v[52:53], off offset:192
	v_add_u32_e32 v180, 64, v50
	v_mad_i64_i32 v[176:177], s[10:11], v180, s37, v[56:57]
	global_load_dwordx4 v[140:143], v[176:177], off
	global_load_dwordx4 v[156:159], v[176:177], off offset:2048
	global_load_dword v173, v[52:53], off offset:256
	v_add_u32_e32 v180, 80, v50
	v_mad_i64_i32 v[176:177], s[10:11], v180, s37, v[56:57]
	global_load_dwordx4 v[144:147], v[176:177], off
	global_load_dwordx4 v[160:163], v[176:177], off offset:2048
	global_load_dword v174, v[52:53], off offset:320
	v_add_u32_e32 v180, 96, v50
	v_mad_i64_i32 v[176:177], s[10:11], v180, s37, v[56:57]
	global_load_dwordx4 v[148:151], v[176:177], off
	global_load_dwordx4 v[164:167], v[176:177], off offset:2048
	global_load_dword v175, v[52:53], off offset:384
	v_add_u32_e32 v180, 112, v50
	v_mad_i64_i32 v[176:177], s[10:11], v180, s37, v[56:57]
	global_load_dwordx4 v[152:155], v[176:177], off
	global_load_dwordx4 v[168:171], v[176:177], off offset:2048
	ds_read_b128 v[76:79], v182 offset:16384
	ds_read_b128 v[80:83], v183 offset:16384
	ds_read_b128 v[84:87], v184 offset:16384
	ds_read_b128 v[88:91], v185 offset:16384
	ds_read_b128 v[92:95], v182 offset:20480
	ds_read_b128 v[96:99], v183 offset:20480
	ds_read_b128 v[100:103], v184 offset:20480
	ds_read_b128 v[104:107], v185 offset:20480
	ds_read_b128 v[108:111], v182 offset:24576
	ds_read_b128 v[112:115], v183 offset:24576
	ds_read_b128 v[116:119], v184 offset:24576
	ds_read_b128 v[120:123], v185 offset:24576
	ds_read_b128 v[124:127], v182 offset:28672
	ds_read_b128 v[128:131], v183 offset:28672
	ds_read_b128 v[132:135], v184 offset:28672
	ds_read_b128 v[136:139], v185 offset:28672
	s_waitcnt vmcnt(9) lgkmcnt(12)
	v_mfma_f32_16x16x32_bf16 v[38:41], v[2:5], v[76:79], 0
	v_mfma_f32_16x16x32_bf16 v[34:37], v[6:9], v[76:79], 0
	v_mfma_f32_16x16x32_bf16 v[38:41], v[10:13], v[80:83], v[38:41]
	v_mfma_f32_16x16x32_bf16 v[34:37], v[14:17], v[80:83], v[34:37]
	v_mfma_f32_16x16x32_bf16 v[38:41], v[18:21], v[84:87], v[38:41]
	v_mfma_f32_16x16x32_bf16 v[34:37], v[22:25], v[84:87], v[34:37]
	v_mfma_f32_16x16x32_bf16 v[38:41], v[26:29], v[88:91], v[38:41]
	v_mfma_f32_16x16x32_bf16 v[34:37], v[30:33], v[88:91], v[34:37]
	v_add_u32_e32 v180, 64, v50
	v_ashrrev_i32_e32 v181, 31, v180
	v_lshlrev_b64 v[178:179], 11, v[180:181]
	v_lshl_add_u64 v[178:179], v[54:55], 0, v[178:179]
	s_nop 7
	v_add_f32_e32 v62, v38, v172
	v_add_f32_e32 v63, v39, v172
	v_lshlrev_b32_e32 v64, 16, v140
	v_and_b32_e32 v65, 0xffff0000, v140
	v_mul_f32_e32 v62, v62, v64
	v_mul_f32_e32 v63, v63, v65
	v_lshlrev_b32_e32 v64, 16, v156
	v_and_b32_e32 v65, 0xffff0000, v156
	v_mul_f32_e32 v62, v62, v64
	v_mul_f32_e32 v63, v63, v65
	v_cvt_pk_bf16_f32 v58, v62, v63
	v_add_f32_e32 v62, v40, v172
	v_add_f32_e32 v63, v41, v172
	v_lshlrev_b32_e32 v64, 16, v141
	v_and_b32_e32 v65, 0xffff0000, v141
	v_mul_f32_e32 v62, v62, v64
	v_mul_f32_e32 v63, v63, v65
	v_lshlrev_b32_e32 v64, 16, v157
	v_and_b32_e32 v65, 0xffff0000, v157
	v_mul_f32_e32 v62, v62, v64
	v_mul_f32_e32 v63, v63, v65
	v_cvt_pk_bf16_f32 v59, v62, v63
	v_add_f32_e32 v62, v34, v172
	v_add_f32_e32 v63, v35, v172
	v_lshlrev_b32_e32 v64, 16, v142
	v_and_b32_e32 v65, 0xffff0000, v142
	v_mul_f32_e32 v62, v62, v64
	v_mul_f32_e32 v63, v63, v65
	v_lshlrev_b32_e32 v64, 16, v158
	v_and_b32_e32 v65, 0xffff0000, v158
	v_mul_f32_e32 v62, v62, v64
	v_mul_f32_e32 v63, v63, v65
	v_cvt_pk_bf16_f32 v60, v62, v63
	v_add_f32_e32 v62, v36, v172
	v_add_f32_e32 v63, v37, v172
	v_lshlrev_b32_e32 v64, 16, v143
	v_and_b32_e32 v65, 0xffff0000, v143
	v_mul_f32_e32 v62, v62, v64
	v_mul_f32_e32 v63, v63, v65
	v_lshlrev_b32_e32 v64, 16, v159
	v_and_b32_e32 v65, 0xffff0000, v159
	v_mul_f32_e32 v62, v62, v64
	v_mul_f32_e32 v63, v63, v65
	v_cvt_pk_bf16_f32 v61, v62, v63
	global_store_dwordx4 v[178:179], v[58:61], off
	s_waitcnt vmcnt(7) lgkmcnt(8)
	v_mfma_f32_16x16x32_bf16 v[38:41], v[2:5], v[92:95], 0
	v_mfma_f32_16x16x32_bf16 v[34:37], v[6:9], v[92:95], 0
	v_mfma_f32_16x16x32_bf16 v[38:41], v[10:13], v[96:99], v[38:41]
	v_mfma_f32_16x16x32_bf16 v[34:37], v[14:17], v[96:99], v[34:37]
	v_mfma_f32_16x16x32_bf16 v[38:41], v[18:21], v[100:103], v[38:41]
	v_mfma_f32_16x16x32_bf16 v[34:37], v[22:25], v[100:103], v[34:37]
	v_mfma_f32_16x16x32_bf16 v[38:41], v[26:29], v[104:107], v[38:41]
	v_mfma_f32_16x16x32_bf16 v[34:37], v[30:33], v[104:107], v[34:37]
	v_add_u32_e32 v180, 80, v50
	v_ashrrev_i32_e32 v181, 31, v180
	v_lshlrev_b64 v[178:179], 11, v[180:181]
	v_lshl_add_u64 v[178:179], v[54:55], 0, v[178:179]
	s_nop 7
	v_add_f32_e32 v62, v38, v173
	v_add_f32_e32 v63, v39, v173
	v_lshlrev_b32_e32 v64, 16, v144
	v_and_b32_e32 v65, 0xffff0000, v144
	v_mul_f32_e32 v62, v62, v64
	v_mul_f32_e32 v63, v63, v65
	v_lshlrev_b32_e32 v64, 16, v160
	v_and_b32_e32 v65, 0xffff0000, v160
	v_mul_f32_e32 v62, v62, v64
	v_mul_f32_e32 v63, v63, v65
	v_cvt_pk_bf16_f32 v58, v62, v63
	v_add_f32_e32 v62, v40, v173
	v_add_f32_e32 v63, v41, v173
	v_lshlrev_b32_e32 v64, 16, v145
	v_and_b32_e32 v65, 0xffff0000, v145
	v_mul_f32_e32 v62, v62, v64
	v_mul_f32_e32 v63, v63, v65
	v_lshlrev_b32_e32 v64, 16, v161
	v_and_b32_e32 v65, 0xffff0000, v161
	v_mul_f32_e32 v62, v62, v64
	v_mul_f32_e32 v63, v63, v65
	v_cvt_pk_bf16_f32 v59, v62, v63
	v_add_f32_e32 v62, v34, v173
	v_add_f32_e32 v63, v35, v173
	v_lshlrev_b32_e32 v64, 16, v146
	v_and_b32_e32 v65, 0xffff0000, v146
	v_mul_f32_e32 v62, v62, v64
	v_mul_f32_e32 v63, v63, v65
	v_lshlrev_b32_e32 v64, 16, v162
	v_and_b32_e32 v65, 0xffff0000, v162
	v_mul_f32_e32 v62, v62, v64
	v_mul_f32_e32 v63, v63, v65
	v_cvt_pk_bf16_f32 v60, v62, v63
	v_add_f32_e32 v62, v36, v173
	v_add_f32_e32 v63, v37, v173
	v_lshlrev_b32_e32 v64, 16, v147
	v_and_b32_e32 v65, 0xffff0000, v147
	v_mul_f32_e32 v62, v62, v64
	v_mul_f32_e32 v63, v63, v65
	v_lshlrev_b32_e32 v64, 16, v163
	v_and_b32_e32 v65, 0xffff0000, v163
	v_mul_f32_e32 v62, v62, v64
	v_mul_f32_e32 v63, v63, v65
	v_cvt_pk_bf16_f32 v61, v62, v63
	global_store_dwordx4 v[178:179], v[58:61], off
	s_waitcnt vmcnt(5) lgkmcnt(4)
	v_mfma_f32_16x16x32_bf16 v[38:41], v[2:5], v[108:111], 0
	v_mfma_f32_16x16x32_bf16 v[34:37], v[6:9], v[108:111], 0
	v_mfma_f32_16x16x32_bf16 v[38:41], v[10:13], v[112:115], v[38:41]
	v_mfma_f32_16x16x32_bf16 v[34:37], v[14:17], v[112:115], v[34:37]
	v_mfma_f32_16x16x32_bf16 v[38:41], v[18:21], v[116:119], v[38:41]
	v_mfma_f32_16x16x32_bf16 v[34:37], v[22:25], v[116:119], v[34:37]
	v_mfma_f32_16x16x32_bf16 v[38:41], v[26:29], v[120:123], v[38:41]
	v_mfma_f32_16x16x32_bf16 v[34:37], v[30:33], v[120:123], v[34:37]
	v_add_u32_e32 v180, 96, v50
	v_ashrrev_i32_e32 v181, 31, v180
	v_lshlrev_b64 v[178:179], 11, v[180:181]
	v_lshl_add_u64 v[178:179], v[54:55], 0, v[178:179]
	s_nop 7
	v_add_f32_e32 v62, v38, v174
	v_add_f32_e32 v63, v39, v174
	v_lshlrev_b32_e32 v64, 16, v148
	v_and_b32_e32 v65, 0xffff0000, v148
	v_mul_f32_e32 v62, v62, v64
	v_mul_f32_e32 v63, v63, v65
	v_lshlrev_b32_e32 v64, 16, v164
	v_and_b32_e32 v65, 0xffff0000, v164
	v_mul_f32_e32 v62, v62, v64
	v_mul_f32_e32 v63, v63, v65
	v_cvt_pk_bf16_f32 v58, v62, v63
	v_add_f32_e32 v62, v40, v174
	v_add_f32_e32 v63, v41, v174
	v_lshlrev_b32_e32 v64, 16, v149
	v_and_b32_e32 v65, 0xffff0000, v149
	v_mul_f32_e32 v62, v62, v64
	v_mul_f32_e32 v63, v63, v65
	v_lshlrev_b32_e32 v64, 16, v165
	v_and_b32_e32 v65, 0xffff0000, v165
	v_mul_f32_e32 v62, v62, v64
	v_mul_f32_e32 v63, v63, v65
	v_cvt_pk_bf16_f32 v59, v62, v63
	v_add_f32_e32 v62, v34, v174
	v_add_f32_e32 v63, v35, v174
	v_lshlrev_b32_e32 v64, 16, v150
	v_and_b32_e32 v65, 0xffff0000, v150
	v_mul_f32_e32 v62, v62, v64
	v_mul_f32_e32 v63, v63, v65
	v_lshlrev_b32_e32 v64, 16, v166
	v_and_b32_e32 v65, 0xffff0000, v166
	v_mul_f32_e32 v62, v62, v64
	v_mul_f32_e32 v63, v63, v65
	v_cvt_pk_bf16_f32 v60, v62, v63
	v_add_f32_e32 v62, v36, v174
	v_add_f32_e32 v63, v37, v174
	v_lshlrev_b32_e32 v64, 16, v151
	v_and_b32_e32 v65, 0xffff0000, v151
	v_mul_f32_e32 v62, v62, v64
	v_mul_f32_e32 v63, v63, v65
	v_lshlrev_b32_e32 v64, 16, v167
	v_and_b32_e32 v65, 0xffff0000, v167
	v_mul_f32_e32 v62, v62, v64
	v_mul_f32_e32 v63, v63, v65
	v_cvt_pk_bf16_f32 v61, v62, v63
	global_store_dwordx4 v[178:179], v[58:61], off
	s_waitcnt vmcnt(3) lgkmcnt(0)
	v_mfma_f32_16x16x32_bf16 v[38:41], v[2:5], v[124:127], 0
	v_mfma_f32_16x16x32_bf16 v[34:37], v[6:9], v[124:127], 0
	v_mfma_f32_16x16x32_bf16 v[38:41], v[10:13], v[128:131], v[38:41]
	v_mfma_f32_16x16x32_bf16 v[34:37], v[14:17], v[128:131], v[34:37]
	v_mfma_f32_16x16x32_bf16 v[38:41], v[18:21], v[132:135], v[38:41]
	v_mfma_f32_16x16x32_bf16 v[34:37], v[22:25], v[132:135], v[34:37]
	v_mfma_f32_16x16x32_bf16 v[38:41], v[26:29], v[136:139], v[38:41]
	v_mfma_f32_16x16x32_bf16 v[34:37], v[30:33], v[136:139], v[34:37]
	v_add_u32_e32 v180, 112, v50
	v_ashrrev_i32_e32 v181, 31, v180
	v_lshlrev_b64 v[178:179], 11, v[180:181]
	v_lshl_add_u64 v[178:179], v[54:55], 0, v[178:179]
	s_nop 7
	v_add_f32_e32 v62, v38, v175
	v_add_f32_e32 v63, v39, v175
	v_lshlrev_b32_e32 v64, 16, v152
	v_and_b32_e32 v65, 0xffff0000, v152
	v_mul_f32_e32 v62, v62, v64
	v_mul_f32_e32 v63, v63, v65
	v_lshlrev_b32_e32 v64, 16, v168
	v_and_b32_e32 v65, 0xffff0000, v168
	v_mul_f32_e32 v62, v62, v64
	v_mul_f32_e32 v63, v63, v65
	v_cvt_pk_bf16_f32 v58, v62, v63
	v_add_f32_e32 v62, v40, v175
	v_add_f32_e32 v63, v41, v175
	v_lshlrev_b32_e32 v64, 16, v153
	v_and_b32_e32 v65, 0xffff0000, v153
	v_mul_f32_e32 v62, v62, v64
	v_mul_f32_e32 v63, v63, v65
	v_lshlrev_b32_e32 v64, 16, v169
	v_and_b32_e32 v65, 0xffff0000, v169
	v_mul_f32_e32 v62, v62, v64
	v_mul_f32_e32 v63, v63, v65
	v_cvt_pk_bf16_f32 v59, v62, v63
	v_add_f32_e32 v62, v34, v175
	v_add_f32_e32 v63, v35, v175
	v_lshlrev_b32_e32 v64, 16, v154
	v_and_b32_e32 v65, 0xffff0000, v154
	v_mul_f32_e32 v62, v62, v64
	v_mul_f32_e32 v63, v63, v65
	v_lshlrev_b32_e32 v64, 16, v170
	v_and_b32_e32 v65, 0xffff0000, v170
	v_mul_f32_e32 v62, v62, v64
	v_mul_f32_e32 v63, v63, v65
	v_cvt_pk_bf16_f32 v60, v62, v63
	v_add_f32_e32 v62, v36, v175
	v_add_f32_e32 v63, v37, v175
	v_lshlrev_b32_e32 v64, 16, v155
	v_and_b32_e32 v65, 0xffff0000, v155
	v_mul_f32_e32 v62, v62, v64
	v_mul_f32_e32 v63, v63, v65
	v_lshlrev_b32_e32 v64, 16, v171
	v_and_b32_e32 v65, 0xffff0000, v171
	v_mul_f32_e32 v62, v62, v64
	v_mul_f32_e32 v63, v63, v65
	v_cvt_pk_bf16_f32 v61, v62, v63
	global_store_dwordx4 v[178:179], v[58:61], off
	s_add_i32 s8, s8, s88
	s_cmp_lt_u32 s8, 0x1000
	s_cbranch_scc1 .Lgm_keep
	s_sub_i32 s0, s8, 0x600
	s_cmp_ge_u32 s8, 0x1600
	s_cselect_b32 s8, s0, 0x7fff
.Lgm_keep:
	s_lshl_b32 s7, s8, 2
	s_cmp_ge_i32 s8, s4
	s_cbranch_scc0 .LBB0_274
